# P5 row loop software-pipelined: next row's y/r/k/v/g loads prefetched into v200-247 at loop top, copied at bottom
# baseline (speedup 1.0000x reference)
; __device__ __forceinline__ float quad_sum(float v) { v += dpp_mov<0xB1>(v); v += dpp_mov<0x4E>(v); return v; }
; __global__ void __launch_bounds__(NT, 2) mk_fwd(Args args) {
;     ...
;         for (int t_ = gw; t_ < MTOK * RMUL(5); t_ += NGW) { const int t = t_ & (MTOK - 1);
;             const size_t o = (size_t)t * 1024 + lane * 16;
;             f32x4 y[4];
; #pragma unroll
;             for (int j = 0; j < 4; ++j) y[j] = *(const f32x4*)(Y + o + 4 * j);
;             float s = 0.f;
; #pragma unroll
;             for (int j = 0; j < 4; ++j) s += (y[j].x + y[j].y) + (y[j].z + y[j].w);
;             s = quad_sum(s); const float mean = s * (1.0f / 64.0f);
;             float s2 = 0.f;
; #pragma unroll
;             for (int j = 0; j < 4; ++j) { y[j] = y[j] - mean; s2 += (y[j].x * y[j].x + y[j].y * y[j].y) + (y[j].z * y[j].z + y[j].w * y[j].w); }
;             s2 = quad_sum(s2); const float rstd = rsqrtf(s2 * (1.0f / 64.0f) + 64e-5f);
;             u32x4 r8[2], k8[2], v8[2], g8[2];
; #pragma unroll
;             for (int j = 0; j < 2; ++j) { r8[j] = *(const u32x4*)(RR + o + 8 * j); k8[j] = *(const u32x4*)(KP + o + 8 * j); v8[j] = *(const u32x4*)(VV + o + 8 * j); g8[j] = *(const u32x4*)(GG + o + 8 * j); }
.LBB0_506:
	s_cmp_lt_i32 s94, 6
	s_cselect_b64 s[0:1], -1, 0
	s_and_b64 s[0:1], s[0:1], s[6:7]
	s_and_b64 s[6:7], s[0:1], s[86:87]
	s_andn2_b64 vcc, exec, s[6:7]
	v_lshlrev_b32_e32 v136, 6, v128
	v_lshlrev_b32_e32 v138, 5, v128
	s_cbranch_vccnz .LBB0_509
	v_readlane_b32 s40, v249, 8
	v_readlane_b32 s48, v249, 16
	v_readlane_b32 s49, v249, 17
	v_mov_b32_e32 v137, 0
	v_readlane_b32 s46, v249, 14
	v_readlane_b32 s47, v249, 15
	v_readlane_b32 s50, v249, 18
	v_readlane_b32 s51, v249, 19
	s_mov_b64 s[8:9], s[48:49]
	v_mbcnt_hi_u32_b32 v61, -1, v169
	s_mov_b64 s[10:11], s[50:51]
	s_mov_b64 s[6:7], s[46:47]
	v_mov_b32_e32 v139, v137
	s_waitcnt vmcnt(0)
	v_and_b32_e32 v0, 64, v61
	v_lshl_add_u64 v[48:49], s[6:7], 0, v[136:137]
	v_lshl_add_u64 v[50:51], s[8:9], 0, v[136:137]
	v_lshl_add_u64 v[52:53], s[10:11], 0, v[136:137]
	v_lshl_add_u64 v[54:55], s[56:57], 0, v[136:137]
	v_lshl_add_u64 v[56:57], s[80:81], 0, v[138:139]
	s_mov_b32 s7, 0
	v_mov_b32_e32 v60, 0x3a27c5ac
	s_mov_b32 s3, 0x800000
	v_xor_b32_e32 v62, 16, v61
	v_add_u32_e32 v63, 64, v0
	v_xor_b32_e32 v64, 32, v61
	v_mov_b32_e32 v65, 0x358637bd
	s_mov_b32 s8, s70
	v_readlane_b32 s41, v249, 9
	v_readlane_b32 s42, v249, 10
	v_readlane_b32 s43, v249, 11
	v_readlane_b32 s44, v249, 12
	v_readlane_b32 s45, v249, 13
	v_readlane_b32 s52, v249, 20
	v_readlane_b32 s53, v249, 21
	v_readlane_b32 s54, v249, 22
	v_readlane_b32 s55, v249, 23
	s_and_b32 s100, s8, 0x3fff
	s_lshl_b32 s101, s100, 12
	s_add_u32 s98, s20, s101
	s_addc_u32 s99, s21, 0
	global_load_dwordx4 v[66:69], v136, s[98:99]
	global_load_dwordx4 v[70:73], v136, s[98:99] offset:16
	global_load_dwordx4 v[74:77], v136, s[98:99] offset:32
	global_load_dwordx4 v[78:81], v136, s[98:99] offset:48
	s_lshl_b32 s101, s100, 11
	s_add_u32 s98, s28, s101
	s_addc_u32 s99, s29, 0
	global_load_dwordx4 v[82:85], v138, s[98:99]
	global_load_dwordx4 v[90:93], v138, s[98:99] offset:16
	s_add_u32 s98, s96, s101
	s_addc_u32 s99, s97, 0
	global_load_dwordx4 v[86:89], v138, s[98:99]
	global_load_dwordx4 v[94:97], v138, s[98:99] offset:16
	s_add_u32 s98, s24, s101
	s_addc_u32 s99, s25, 0
	global_load_dwordx4 v[98:101], v138, s[98:99]
	global_load_dwordx4 v[106:109], v138, s[98:99] offset:16
	s_add_u32 s98, s26, s101
	s_addc_u32 s99, s27, 0
	global_load_dwordx4 v[102:105], v138, s[98:99]
	global_load_dwordx4 v[110:113], v138, s[98:99] offset:16
	s_waitcnt vmcnt(0)
.LBB0_508:
	s_and_b32 s6, s8, 0x3fff
	v_cmp_lt_i32_e32 vcc, v62, v63
	s_lshl_b32 s6, s6, 12
	v_cndmask_b32_e32 v58, v61, v62, vcc
	v_cmp_lt_i32_e32 vcc, v64, v63
	v_cndmask_b32_e32 v59, v61, v64, vcc
	global_load_dwordx4 v[0:3], v[48:49], off offset:48
	global_load_dwordx4 v[4:7], v[48:49], off offset:32
	global_load_dwordx4 v[8:11], v[48:49], off offset:16
	global_load_dwordx4 v[12:15], v[48:49], off
	global_load_dwordx4 v[16:19], v[50:51], off
	global_load_dwordx4 v[28:31], v[50:51], off offset:16
	global_load_dwordx4 v[20:23], v[52:53], off
	global_load_dwordx4 v[24:27], v[52:53], off offset:16
	global_load_dwordx4 v[36:39], v[50:51], off offset:32
	global_load_dwordx4 v[40:43], v[50:51], off offset:48
	global_load_dwordx4 v[44:47], v[52:53], off offset:32
	global_load_dwordx4 v[32:35], v[52:53], off offset:48
	v_lshlrev_b32_e32 v129, 2, v58
	v_lshlrev_b32_e32 v131, 2, v59
	v_lshl_add_u64 v[58:59], v[56:57], 0, s[6:7]
	s_nop 0
	global_load_dwordx4 v[114:117], v[58:59], off offset:16
	global_load_dwordx4 v[118:121], v[58:59], off
	s_add_i32 s8, s8, s72
	s_and_b32 s100, s8, 0x3fff
	s_lshl_b32 s101, s100, 12
	s_add_u32 s98, s20, s101
	s_addc_u32 s99, s21, 0
	global_load_dwordx4 v[200:203], v136, s[98:99]
	global_load_dwordx4 v[204:207], v136, s[98:99] offset:16
	global_load_dwordx4 v[208:211], v136, s[98:99] offset:32
	global_load_dwordx4 v[212:215], v136, s[98:99] offset:48
	s_lshl_b32 s101, s100, 11
	s_add_u32 s98, s28, s101
	s_addc_u32 s99, s29, 0
	global_load_dwordx4 v[216:219], v138, s[98:99]
	global_load_dwordx4 v[224:227], v138, s[98:99] offset:16
	s_add_u32 s98, s96, s101
	s_addc_u32 s99, s97, 0
	global_load_dwordx4 v[220:223], v138, s[98:99]
	global_load_dwordx4 v[228:231], v138, s[98:99] offset:16
	s_add_u32 s98, s24, s101
	s_addc_u32 s99, s25, 0
	global_load_dwordx4 v[232:235], v138, s[98:99]
	global_load_dwordx4 v[240:243], v138, s[98:99] offset:16
	s_add_u32 s98, s26, s101
	s_addc_u32 s99, s27, 0
	global_load_dwordx4 v[236:239], v138, s[98:99]
	global_load_dwordx4 v[244:247], v138, s[98:99] offset:16
	s_waitcnt vmcnt(14)
; __device__ __forceinline__ float bf_lo(unsigned u) { return __uint_as_float(u << 16); }
; __device__ __forceinline__ float bf_hi(unsigned u) { return __uint_as_float(u & 0xffff0000u); }
; __device__ __forceinline__ float quad_sum(float v) { v += dpp_mov<0xB1>(v); v += dpp_mov<0x4E>(v); return v; }
; __global__ void __launch_bounds__(NT, 2) mk_fwd(Args args) {
;     ...
;             for (int j = 0; j < 4; ++j) y[j] = *(const f32x4*)(Y + o + 4 * j);
;             float s = 0.f;
; #pragma unroll
;             for (int j = 0; j < 4; ++j) s += (y[j].x + y[j].y) + (y[j].z + y[j].w);
;             s = quad_sum(s); const float mean = s * (1.0f / 64.0f);
;             float s2 = 0.f;
; #pragma unroll
;             for (int j = 0; j < 4; ++j) { y[j] = y[j] - mean; s2 += (y[j].x * y[j].x + y[j].y * y[j].y) + (y[j].z * y[j].z + y[j].w * y[j].w); }
;             s2 = quad_sum(s2); const float rstd = rsqrtf(s2 * (1.0f / 64.0f) + 64e-5f);
;             u32x4 r8[2], k8[2], v8[2], g8[2];
; #pragma unroll
;             for (int j = 0; j < 2; ++j) { r8[j] = *(const u32x4*)(RR + o + 8 * j); k8[j] = *(const u32x4*)(KP + o + 8 * j); v8[j] = *(const u32x4*)(VV + o + 8 * j); g8[j] = *(const u32x4*)(GG + o + 8 * j); }
;             float dp = 0.f;
; #pragma unroll
;             for (int j = 0; j < 2; ++j)
; #pragma unroll
;                 for (int e = 0; e < 4; ++e) { const int col = lane * 16 + j * 8 + e * 2; dp += bf_lo(r8[j][e]) * bf_lo(k8[j][e]) * rk[col] + bf_hi(r8[j][e]) * bf_hi(k8[j][e]) * rk[col + 1]; }
;             dp = quad_sum(dp);
	v_mov_b32_e32 v142, v66
	v_mov_b32_e32 v143, v69
	v_mov_b32_e32 v144, v71
	v_mov_b32_e32 v122, v13
	v_mov_b32_e32 v123, v14
	v_mov_b32_e32 v13, v15
	v_mov_b32_e32 v14, v67
	v_mov_b32_e32 v15, v68
	v_mov_b32_e32 v145, v72
	v_mov_b32_e32 v146, v70
	v_mov_b32_e32 v147, v73
	v_mov_b32_e32 v140, v1
	v_mov_b32_e32 v1, v3
	v_and_b32_e32 v154, 0xffff0000, v82
	v_lshlrev_b32_e32 v155, 16, v83
	v_and_b32_e32 v156, 0xffff0000, v86
	v_lshlrev_b32_e32 v157, 16, v87
	v_lshlrev_b32_e32 v82, 16, v82
	v_and_b32_e32 v83, 0xffff0000, v83
	v_lshlrev_b32_e32 v86, 16, v86
	v_and_b32_e32 v87, 0xffff0000, v87
	v_lshlrev_b32_e32 v137, 16, v99
	v_and_b32_e32 v172, 0xffff0000, v99
	v_lshlrev_b32_e32 v190, 16, v108
	v_and_b32_e32 v192, 0xffff0000, v108
	v_lshlrev_b32_e32 v99, 16, v109
	v_and_b32_e32 v3, 0xffff0000, v109
	v_pk_add_f32 v[14:15], v[14:15], v[142:143]
	v_pk_add_f32 v[108:109], v[144:145], v[146:147]
	v_mov_b32_e32 v126, v5
	v_mov_b32_e32 v5, v7
	v_pk_mul_f32 v[82:83], v[82:83], v[86:87]
	v_add_f32_e32 v7, v14, v15
	v_pk_add_f32 v[14:15], v[108:109], v[108:109] op_sel:[0,1] op_sel_hi:[1,0]
	v_add_f32_e32 v148, v74, v75
	v_add_f32_e32 v150, v76, v77
	v_mov_b32_e32 v153, v78
	v_mov_b32_e32 v149, v80
	v_mov_b32_e32 v151, v81
	v_and_b32_e32 v158, 0xffff0000, v84
	v_lshlrev_b32_e32 v159, 16, v85
	v_and_b32_e32 v160, 0xffff0000, v88
	v_lshlrev_b32_e32 v161, 16, v89
	v_lshlrev_b32_e32 v84, 16, v84
	v_and_b32_e32 v85, 0xffff0000, v85
	v_lshlrev_b32_e32 v88, 16, v88
	v_and_b32_e32 v89, 0xffff0000, v89
	v_lshlrev_b32_e32 v191, 16, v112
	v_and_b32_e32 v193, 0xffff0000, v112
	v_lshlrev_b32_e32 v194, 16, v113
	v_and_b32_e32 v195, 0xffff0000, v113
	v_pk_mul_f32 v[112:113], v[154:155], v[156:157]
	v_pk_mul_f32 v[12:13], v[12:13], v[82:83]
	v_add_f32_e32 v152, 0, v7
	v_mov_b32_e32 v15, v79
	v_mov_b32_e32 v124, v9
	v_mov_b32_e32 v9, v11
	v_lshlrev_b32_e32 v183, 16, v110
	v_and_b32_e32 v185, 0xffff0000, v110
	v_lshlrev_b32_e32 v187, 16, v111
	v_and_b32_e32 v189, 0xffff0000, v111
	v_pk_add_f32 v[110:111], v[148:149], v[150:151]
	v_pk_mul_f32 v[84:85], v[84:85], v[88:89]
	v_pk_fma_f32 v[12:13], v[122:123], v[112:113], v[12:13]
	v_pk_add_f32 v[14:15], v[152:153], v[14:15]
	v_mov_b32_e32 v125, v10
	v_and_b32_e32 v162, 0xffff0000, v90
	v_lshlrev_b32_e32 v163, 16, v91
	v_and_b32_e32 v164, 0xffff0000, v94
	v_lshlrev_b32_e32 v165, 16, v95
	v_lshlrev_b32_e32 v90, 16, v90
	v_and_b32_e32 v91, 0xffff0000, v91
	v_lshlrev_b32_e32 v94, 16, v94
	v_and_b32_e32 v95, 0xffff0000, v95
	v_pk_mul_f32 v[86:87], v[158:159], v[160:161]
	v_pk_mul_f32 v[8:9], v[8:9], v[84:85]
	v_add_f32_e32 v7, 0, v12
	v_pk_add_f32 v[14:15], v[14:15], v[110:111]
	v_pk_mul_f32 v[90:91], v[90:91], v[94:95]
	v_pk_fma_f32 v[8:9], v[124:125], v[86:87], v[8:9]
	v_add_f32_e32 v7, v7, v13
	v_add_f32_e32 v12, v14, v15
	v_mov_b32_e32 v127, v6
	v_and_b32_e32 v166, 0xffff0000, v92
	v_lshlrev_b32_e32 v167, 16, v93
	v_and_b32_e32 v170, 0xffff0000, v96
	v_lshlrev_b32_e32 v171, 16, v97
	v_lshlrev_b32_e32 v92, 16, v92
	v_and_b32_e32 v93, 0xffff0000, v93
	v_lshlrev_b32_e32 v96, 16, v96
	v_and_b32_e32 v97, 0xffff0000, v97
	v_pk_mul_f32 v[88:89], v[162:163], v[164:165]
	v_pk_mul_f32 v[4:5], v[4:5], v[90:91]
	v_add_f32_e32 v7, v7, v8
	v_add_f32_dpp v8, v12, v12 quad_perm:[1,0,3,2] row_mask:0xf bank_mask:0xf bound_ctrl:1
	v_mov_b32_e32 v10, v17
	v_pk_mul_f32 v[92:93], v[92:93], v[96:97]
	v_pk_fma_f32 v[4:5], v[126:127], v[88:89], v[4:5]
	v_add_f32_e32 v7, v7, v9
	v_add_f32_dpp v17, v8, v8 quad_perm:[2,3,0,1] row_mask:0xf bank_mask:0xf bound_ctrl:1
	v_mov_b32_e32 v141, v2
	v_pk_mul_f32 v[94:95], v[166:167], v[170:171]
	v_pk_mul_f32 v[0:1], v[0:1], v[92:93]
	v_add_f32_e32 v4, v7, v4
	v_fmamk_f32 v9, v17, 0xbc800000, v67
	v_fmamk_f32 v8, v17, 0xbc800000, v66
	v_fmamk_f32 v69, v17, 0xbc800000, v69
	v_fmac_f32_e32 v68, 0xbc800000, v17
	v_fmamk_f32 v13, v17, 0xbc800000, v71
	v_fmamk_f32 v12, v17, 0xbc800000, v70
	v_fmamk_f32 v73, v17, 0xbc800000, v73
	v_fmac_f32_e32 v72, 0xbc800000, v17
	v_pk_fma_f32 v[0:1], v[140:141], v[94:95], v[0:1]
	v_fmamk_f32 v15, v17, 0xbc800000, v75
	v_fmamk_f32 v14, v17, 0xbc800000, v74
	v_add_f32_e32 v7, v4, v5
	v_pk_mul_f32 v[4:5], v[68:69], v[68:69]
	v_pk_mul_f32 v[66:67], v[8:9], v[8:9]
	v_pk_mul_f32 v[70:71], v[72:73], v[72:73]
	v_pk_mul_f32 v[74:75], v[12:13], v[12:13]
	v_fmamk_f32 v77, v17, 0xbc800000, v77
	v_add_f32_e32 v0, v7, v0
	v_pk_mov_b32 v[82:83], v[66:67], v[4:5] op_sel:[1,0]
	v_mov_b32_e32 v67, v5
	v_pk_mov_b32 v[4:5], v[74:75], v[70:71] op_sel:[1,0]
	v_mov_b32_e32 v75, v71
	v_mov_b32_e32 v6, v20
	v_fmac_f32_e32 v76, 0xbc800000, v17
	v_fmamk_f32 v84, v17, 0xbc800000, v81
	v_fmamk_f32 v85, v17, 0xbc800000, v80
	v_fmamk_f32 v79, v17, 0xbc800000, v79
	v_fmac_f32_e32 v78, 0xbc800000, v17
	v_mul_f32_e32 v20, v15, v15
	v_mul_f32_e32 v80, v77, v77
	v_add_f32_e32 v7, v0, v1
	v_pk_add_f32 v[0:1], v[82:83], v[66:67]
	v_pk_add_f32 v[4:5], v[4:5], v[74:75]
	v_mul_f32_e32 v86, v78, v78
	v_mul_f32_e32 v87, v79, v79
	v_mul_f32_e32 v17, v85, v85
	v_mul_f32_e32 v88, v84, v84
	v_pk_fma_f32 v[70:71], v[14:15], v[14:15], v[20:21] op_sel_hi:[1,1,0]
	v_pk_fma_f32 v[80:81], v[76:77], v[76:77], v[80:81] op_sel_hi:[1,1,0]
	v_pk_add_f32 v[0:1], v[0:1], v[0:1] op_sel:[0,1] op_sel_hi:[1,0]
	v_pk_add_f32 v[4:5], v[4:5], v[4:5] op_sel:[0,1] op_sel_hi:[1,0]
	v_mov_b32_e32 v71, v17
	v_mov_b32_e32 v81, v88
	v_mov_b32_e32 v1, v86
	v_mov_b32_e32 v5, v87
	v_pk_add_f32 v[66:67], v[70:71], v[80:81]
	v_pk_add_f32 v[0:1], v[0:1], v[4:5]
	v_add_f32_dpp v17, v7, v7 quad_perm:[1,0,3,2] row_mask:0xf bank_mask:0xf bound_ctrl:1
	v_pk_add_f32 v[0:1], v[0:1], v[66:67]
	v_mov_b32_e32 v2, v43
	v_add_f32_e32 v0, v0, v1
; __device__ __forceinline__ float bf_lo(unsigned u) { return __uint_as_float(u << 16); }
; __device__ __forceinline__ float bf_hi(unsigned u) { return __uint_as_float(u & 0xffff0000u); }
; __device__ __forceinline__ unsigned pk2(float lo, float hi) { return pg8::cvt_pk_bf16(lo, hi); }
; __device__ __forceinline__ float quad_sum(float v) { v += dpp_mov<0xB1>(v); v += dpp_mov<0x4E>(v); return v; }
; __global__ void __launch_bounds__(NT, 2) mk_fwd(Args args) {
;     ...
;             s2 = quad_sum(s2); const float rstd = rsqrtf(s2 * (1.0f / 64.0f) + 64e-5f);
;             u32x4 r8[2], k8[2], v8[2], g8[2];
; #pragma unroll
;             for (int j = 0; j < 2; ++j) { r8[j] = *(const u32x4*)(RR + o + 8 * j); k8[j] = *(const u32x4*)(KP + o + 8 * j); v8[j] = *(const u32x4*)(VV + o + 8 * j); g8[j] = *(const u32x4*)(GG + o + 8 * j); }
;             float dp = 0.f;
; #pragma unroll
;             for (int j = 0; j < 2; ++j)
; #pragma unroll
;                 for (int e = 0; e < 4; ++e) { const int col = lane * 16 + j * 8 + e * 2; dp += bf_lo(r8[j][e]) * bf_lo(k8[j][e]) * rk[col] + bf_hi(r8[j][e]) * bf_hi(k8[j][e]) * rk[col + 1]; }
;             dp = quad_sum(dp);
;             u32x4 ov[2];
; #pragma unroll
;             for (int j = 0; j < 2; ++j)
; #pragma unroll
;                 for (int e = 0; e < 4; ++e) { const int c = j * 8 + e * 2; const int col = lane * 16 + c;
;                     const float y0 = y[c >> 2][c & 3], y1 = y[(c + 1) >> 2][(c + 1) & 3];
;                     const float o0 = (y0 * rstd * lng[col] + lnb[col] + dp * bf_lo(v8[j][e])) * bf_lo(g8[j][e]);
;                     const float o1 = (y1 * rstd * lng[col + 1] + lnb[col + 1] + dp * bf_hi(v8[j][e])) * bf_hi(g8[j][e]);
;                     ov[j][e] = pk2(o0, o1); }
;             bf16* op = HB + (size_t)t * DM + 1024 + lane * 16;
;             *(u32x4*)op = ov[0]; *(u32x4*)(op + 8) = ov[1];
;     ...
;                     for (int e = 0; e < 4; ++e) { const int col = lane * 16 + j * 8 + e * 2; ya[j][e] = pk2(bf_lo(ya[j][e]) * ri * og[col], bf_hi(ya[j][e]) * ri * og[col + 1]); }
	v_mov_b32_dpp v7, v17 quad_perm:[2,3,0,1] row_mask:0xf bank_mask:0xf bound_ctrl:1
	v_lshlrev_b32_e32 v43, 16, v98
	v_add_f32_dpp v0, v0, v0 quad_perm:[1,0,3,2] row_mask:0xf bank_mask:0xf bound_ctrl:1
	v_and_b32_e32 v176, 0xffff0000, v100
	v_lshlrev_b32_e32 v178, 16, v101
	v_add_f32_dpp v0, v0, v0 quad_perm:[2,3,0,1] row_mask:0xf bank_mask:0xf bound_ctrl:1
	v_fmamk_f32 v0, v0, 0x3c800000, v60
	v_mul_f32_e32 v1, 0x4b800000, v0
	v_cmp_gt_f32_e32 vcc, s3, v0
	v_lshlrev_b32_e32 v182, 16, v106
	v_lshlrev_b32_e32 v133, 16, v102
	v_cndmask_b32_e32 v0, v0, v1, vcc
	v_rsq_f32_e32 v0, v0
	v_and_b32_e32 v11, 0xffff0000, v98
	v_lshlrev_b32_e32 v139, 16, v103
	v_and_b32_e32 v173, 0xffff0000, v103
	v_mul_f32_e32 v1, 0x45800000, v0
	v_cndmask_b32_e32 v4, v0, v1, vcc
	v_mul_f32_e32 v0, v4, v8
	v_mul_f32_e32 v1, v4, v68
	v_mul_f32_e32 v5, v4, v69
	v_mul_f32_e32 v8, v4, v12
	v_mul_f32_e32 v12, v4, v13
	v_mul_f32_e32 v13, v4, v72
	v_mul_f32_e32 v14, v4, v14
	v_mul_f32_e32 v16, v16, v0
	v_mul_f32_e32 v20, v4, v73
	v_mul_f32_e32 v15, v4, v15
	v_fma_f32 v18, v18, v1, v22
	v_fmac_f32_e32 v23, v5, v19
	v_fma_f32 v5, v28, v8, v24
	v_fma_f32 v8, v12, v29, v25
	v_fma_f32 v12, v30, v13, v26
	v_fma_f32 v13, v36, v14, v44
	v_pk_add_f32 v[0:1], v[6:7], v[16:17]
	v_lshlrev_b32_e32 v174, 16, v100
	v_and_b32_e32 v177, 0xffff0000, v104
	v_lshlrev_b32_e32 v179, 16, v105
	v_and_b32_e32 v180, 0xffff0000, v101
	v_and_b32_e32 v184, 0xffff0000, v106
	v_fmac_f32_e32 v27, v20, v31
	v_fma_f32 v14, v15, v37, v45
	v_fma_f32 v6, v1, v43, v0
	v_mul_f32_e32 v0, v4, v9
	v_fmac_f32_e32 v18, v1, v137
	v_fmac_f32_e32 v23, v1, v172
	v_fmac_f32_e32 v8, v1, v176
	v_fmac_f32_e32 v12, v1, v178
	v_fmac_f32_e32 v13, v1, v182
	v_lshlrev_b32_e32 v175, 16, v104
	v_and_b32_e32 v181, 0xffff0000, v105
	v_mul_f32_e32 v66, v4, v76
	v_mul_f32_e32 v67, v4, v77
	v_mul_f32_e32 v68, v4, v78
	v_mul_f32_e32 v69, v4, v79
	v_mul_f32_e32 v98, v4, v85
	v_fmac_f32_e32 v5, v1, v174
	v_fmac_f32_e32 v27, v1, v180
	v_fmac_f32_e32 v14, v1, v184
	v_mul_f32_e32 v16, v6, v133
	v_pk_mul_f32 v[10:11], v[0:1], v[10:11]
	v_mul_f32_e32 v6, v18, v139
	v_mul_f32_e32 v7, v23, v173
	v_mul_f32_e32 v8, v8, v177
	v_mul_f32_e32 v12, v12, v179
	v_mul_f32_e32 v13, v13, v183
	v_mov_b32_e32 v0, v42
	v_lshlrev_b32_e32 v186, 16, v107
	v_and_b32_e32 v188, 0xffff0000, v107
	v_fma_f32 v15, v38, v66, v46
	v_fmac_f32_e32 v47, v67, v39
	v_fma_f32 v19, v40, v68, v32
	v_fma_f32 v20, v69, v41, v33
	v_mul_f32_e32 v9, v5, v175
	v_mul_f32_e32 v17, v27, v181
	v_mul_f32_e32 v14, v14, v185
	v_cvt_pk_bf16_f32 v5, v6, v7
	v_cvt_pk_bf16_f32 v6, v9, v8
	v_cvt_pk_bf16_f32 v7, v12, v17
	v_cvt_pk_bf16_f32 v8, v13, v14
	v_pk_mul_f32 v[12:13], v[0:1], v[98:99]
	v_mul_f32_e32 v0, v4, v84
	v_fmac_f32_e32 v15, v1, v186
	v_fmac_f32_e32 v47, v1, v188
	v_fmac_f32_e32 v19, v1, v190
	v_fmac_f32_e32 v20, v1, v192
	v_add_f32_e32 v21, v10, v21
	v_pk_mul_f32 v[0:1], v[0:1], v[2:3]
	v_and_b32_e32 v135, 0xffff0000, v102
	v_add_f32_e32 v4, v21, v11
	v_add_f32_e32 v11, v34, v12
	v_add_f32_e32 v0, v0, v35
	v_mul_f32_e32 v2, v4, v135
	v_add_f32_e32 v3, v11, v13
	v_add_f32_e32 v0, v0, v1
	v_mul_f32_e32 v15, v15, v187
	v_mul_f32_e32 v18, v47, v189
	v_mul_f32_e32 v19, v19, v191
	v_mul_f32_e32 v20, v20, v193
	v_cvt_pk_bf16_f32 v9, v15, v18
	v_cvt_pk_bf16_f32 v10, v19, v20
	v_cvt_pk_bf16_f32 v4, v16, v2
	v_mul_f32_e32 v2, v3, v194
	v_mul_f32_e32 v0, v0, v195
	global_store_dwordx4 v[58:59], v[4:7], off offset:2048
	v_cvt_pk_bf16_f32 v11, v2, v0
	global_store_dwordx4 v[58:59], v[8:11], off offset:2064
	global_load_dwordx4 v[0:3], v[54:55], off
	global_load_dwordx4 v[4:7], v[54:55], off offset:16
	s_nop 0
	global_load_dwordx4 v[8:11], v[54:55], off offset:32
	global_load_dwordx4 v[12:15], v[54:55], off offset:48
	s_waitcnt vmcnt(16)
; __device__ __forceinline__ float bf_lo(unsigned u) { return __uint_as_float(u << 16); }
; __device__ __forceinline__ float bf_hi(unsigned u) { return __uint_as_float(u & 0xffff0000u); }
; __device__ __forceinline__ unsigned pk2(float lo, float hi) { return pg8::cvt_pk_bf16(lo, hi); }
; __device__ __forceinline__ float wave_sum(float v) { v = row16_sum(v); v += __shfl_xor(v, 16); v += __shfl_xor(v, 32); return v; }
; __global__ void __launch_bounds__(NT, 2) mk_fwd(Args args) {
;     ...
;             {
;                 bf16* ap = HB + (size_t)t * DM + lane * 16; u32x4 ya[2]; ya[0] = *(const u32x4*)ap; ya[1] = *(const u32x4*)(ap + 8);
;                 float q2 = 0.f;
; #pragma unroll
;                 for (int j = 0; j < 2; ++j)
; #pragma unroll
;                     for (int e = 0; e < 4; ++e) { const float v0 = bf_lo(ya[j][e]), v1 = bf_hi(ya[j][e]); q2 += v0 * v0 + v1 * v1; }
;                 q2 = wave_sum(q2);
;                 const float ri = rsqrtf(q2 * (1.0f / 1024.0f) + 1e-6f);
; #pragma unroll
;                 for (int j = 0; j < 2; ++j)
; #pragma unroll
;                     for (int e = 0; e < 4; ++e) { const int col = lane * 16 + j * 8 + e * 2; ya[j][e] = pk2(bf_lo(ya[j][e]) * ri * og[col], bf_hi(ya[j][e]) * ri * og[col + 1]); }
;                 *(u32x4*)ap = ya[0]; *(u32x4*)(ap + 8) = ya[1];
;             }
;         }
	v_lshlrev_b32_e32 v196, 16, v118
	v_and_b32_e32 v118, 0xffff0000, v118
	v_lshlrev_b32_e32 v197, 16, v119
	v_and_b32_e32 v119, 0xffff0000, v119
	v_lshlrev_b32_e32 v198, 16, v120
	v_and_b32_e32 v120, 0xffff0000, v120
	v_lshlrev_b32_e32 v100, 16, v114
	v_lshlrev_b32_e32 v101, 16, v115
	v_and_b32_e32 v103, 0xffff0000, v115
	v_and_b32_e32 v102, 0xffff0000, v114
	v_mul_f32_e32 v114, v118, v118
	v_mul_f32_e32 v115, v119, v119
	v_lshlrev_b32_e32 v199, 16, v121
	v_and_b32_e32 v121, 0xffff0000, v121
	v_lshlrev_b32_e32 v104, 16, v116
	v_and_b32_e32 v106, 0xffff0000, v116
	v_mul_f32_e32 v116, v120, v120
	v_fmac_f32_e32 v114, v196, v196
	v_fmac_f32_e32 v115, v197, v197
	v_lshlrev_b32_e32 v105, 16, v117
	v_and_b32_e32 v107, 0xffff0000, v117
	v_mul_f32_e32 v117, v121, v121
	v_fmac_f32_e32 v116, v198, v198
	v_add_f32_e32 v20, v114, v115
	v_pk_mul_f32 v[96:97], v[102:103], v[102:103]
	v_fmac_f32_e32 v117, v199, v199
	v_add_f32_e32 v20, v20, v116
	v_pk_fma_f32 v[18:19], v[100:101], v[100:101], v[96:97]
	v_add_f32_e32 v20, v20, v117
	v_pk_mul_f32 v[16:17], v[106:107], v[106:107]
	v_add_f32_e32 v18, v20, v18
	v_pk_fma_f32 v[16:17], v[104:105], v[104:105], v[16:17]
	v_add_f32_e32 v18, v18, v19
	v_add_f32_e32 v16, v18, v16
	v_add_f32_e32 v16, v16, v17
	s_nop 1
	v_add_f32_dpp v16, v16, v16 quad_perm:[1,0,3,2] row_mask:0xf bank_mask:0xf bound_ctrl:1
	s_nop 1
	v_add_f32_dpp v16, v16, v16 quad_perm:[2,3,0,1] row_mask:0xf bank_mask:0xf bound_ctrl:1
	s_nop 1
	v_add_f32_dpp v16, v16, v16 row_half_mirror row_mask:0xf bank_mask:0xf bound_ctrl:1
	s_nop 1
	v_add_f32_dpp v16, v16, v16 row_mirror row_mask:0xf bank_mask:0xf bound_ctrl:1
	ds_bpermute_b32 v17, v129, v16
	s_waitcnt lgkmcnt(0)
	v_add_f32_e32 v16, v16, v17
	ds_bpermute_b32 v17, v131, v16
	s_waitcnt lgkmcnt(0)
	v_add_f32_e32 v16, v16, v17
	v_fmamk_f32 v16, v16, 0x3a800000, v65
	v_mul_f32_e32 v17, 0x4b800000, v16
	v_cmp_gt_f32_e32 vcc, s3, v16
	s_nop 1
	v_cndmask_b32_e32 v16, v16, v17, vcc
	v_rsq_f32_e32 v16, v16
	s_nop 0
	v_mul_f32_e32 v17, 0x45800000, v16
	v_cndmask_b32_e32 v16, v16, v17, vcc
	v_mul_f32_e32 v17, v16, v196
	v_mul_f32_e32 v18, v16, v118
	v_mul_f32_e32 v19, v16, v197
	v_mul_f32_e32 v20, v16, v119
	v_mul_f32_e32 v21, v16, v198
	v_mul_f32_e32 v22, v16, v120
	v_mul_f32_e32 v23, v16, v199
	v_mul_f32_e32 v24, v16, v121
	s_waitcnt vmcnt(3)
	v_mul_f32_e32 v0, v0, v17
	v_mul_f32_e32 v1, v1, v18
	v_mul_f32_e32 v2, v2, v19
	v_mul_f32_e32 v3, v3, v20
	v_mul_f32_e32 v25, v16, v100
	v_mul_f32_e32 v26, v16, v102
	v_mul_f32_e32 v27, v16, v101
	v_mul_f32_e32 v28, v16, v103
	v_mul_f32_e32 v29, v16, v104
	v_mul_f32_e32 v30, v16, v106
	v_mul_f32_e32 v31, v16, v105
	v_mul_f32_e32 v16, v16, v107
	s_waitcnt vmcnt(2)
	v_mul_f32_e32 v4, v4, v21
	v_mul_f32_e32 v5, v5, v22
	v_mul_f32_e32 v6, v6, v23
	v_mul_f32_e32 v7, v7, v24
	v_cvt_pk_bf16_f32 v0, v0, v1
	v_cvt_pk_bf16_f32 v1, v2, v3
	v_cvt_pk_bf16_f32 v2, v4, v5
	v_cvt_pk_bf16_f32 v3, v6, v7
	s_waitcnt vmcnt(1)
	v_mul_f32_e32 v8, v8, v25
	v_mul_f32_e32 v9, v9, v26
	v_mul_f32_e32 v10, v10, v27
	v_mul_f32_e32 v11, v11, v28
	s_waitcnt vmcnt(0)
	v_mul_f32_e32 v12, v12, v29
	v_mul_f32_e32 v13, v13, v30
	v_mul_f32_e32 v14, v14, v31
	v_mul_f32_e32 v15, v15, v16
	v_cvt_pk_bf16_f32 v4, v8, v9
	v_cvt_pk_bf16_f32 v5, v10, v11
	v_cvt_pk_bf16_f32 v6, v12, v13
	v_cvt_pk_bf16_f32 v7, v14, v15
	v_mov_b32_e32 v66, v200
	v_mov_b32_e32 v67, v201
	v_mov_b32_e32 v68, v202
	v_mov_b32_e32 v69, v203
	v_mov_b32_e32 v70, v204
	v_mov_b32_e32 v71, v205
	v_mov_b32_e32 v72, v206
	v_mov_b32_e32 v73, v207
	v_mov_b32_e32 v74, v208
	v_mov_b32_e32 v75, v209
	v_mov_b32_e32 v76, v210
	v_mov_b32_e32 v77, v211
	v_mov_b32_e32 v78, v212
	v_mov_b32_e32 v79, v213
	v_mov_b32_e32 v80, v214
	v_mov_b32_e32 v81, v215
	v_mov_b32_e32 v82, v216
	v_mov_b32_e32 v83, v217
	v_mov_b32_e32 v84, v218
	v_mov_b32_e32 v85, v219
	v_mov_b32_e32 v86, v220
	v_mov_b32_e32 v87, v221
	v_mov_b32_e32 v88, v222
	v_mov_b32_e32 v89, v223
	v_mov_b32_e32 v90, v224
	v_mov_b32_e32 v91, v225
	v_mov_b32_e32 v92, v226
	v_mov_b32_e32 v93, v227
	v_mov_b32_e32 v94, v228
	v_mov_b32_e32 v95, v229
	v_mov_b32_e32 v96, v230
	v_mov_b32_e32 v97, v231
	v_mov_b32_e32 v98, v232
	v_mov_b32_e32 v99, v233
	v_mov_b32_e32 v100, v234
	v_mov_b32_e32 v101, v235
	v_mov_b32_e32 v102, v236
	v_mov_b32_e32 v103, v237
	v_mov_b32_e32 v104, v238
	v_mov_b32_e32 v105, v239
	v_mov_b32_e32 v106, v240
	v_mov_b32_e32 v107, v241
	v_mov_b32_e32 v108, v242
	v_mov_b32_e32 v109, v243
	v_mov_b32_e32 v110, v244
	v_mov_b32_e32 v111, v245
	v_mov_b32_e32 v112, v246
	v_mov_b32_e32 v113, v247
	global_store_dwordx4 v[58:59], v[0:3], off
	global_store_dwordx4 v[58:59], v[4:7], off offset:16
	s_cmpk_lt_i32 s8, 0x4000
	s_cbranch_scc1 .LBB0_508

; __global__ void __launch_bounds__(NT, 2) mk_fwd(Args args) {
	.amdhsa_kernel _Z6mk_fwd4Args
		.amdhsa_group_segment_fixed_size 0
		.amdhsa_private_segment_fixed_size 0
		.amdhsa_kernarg_size 512
		.amdhsa_user_sgpr_count 2
		.amdhsa_user_sgpr_dispatch_ptr 0
		.amdhsa_user_sgpr_queue_ptr 0
		.amdhsa_user_sgpr_kernarg_segment_ptr 1
		.amdhsa_user_sgpr_dispatch_id 0
		.amdhsa_user_sgpr_kernarg_preload_length 0
		.amdhsa_user_sgpr_kernarg_preload_offset 0
		.amdhsa_user_sgpr_private_segment_size 0
		.amdhsa_uses_dynamic_stack 0
		.amdhsa_enable_private_segment 0
		.amdhsa_system_sgpr_workgroup_id_x 1
		.amdhsa_system_sgpr_workgroup_id_y 0
		.amdhsa_system_sgpr_workgroup_id_z 0
		.amdhsa_system_sgpr_workgroup_info 0
		.amdhsa_system_vgpr_workitem_id 2
		.amdhsa_next_free_vgpr 250
		.amdhsa_next_free_sgpr 102
		.amdhsa_accum_offset 252
		.amdhsa_reserve_vcc 1
		.amdhsa_float_round_mode_32 0
		.amdhsa_float_round_mode_16_64 0
		.amdhsa_float_denorm_mode_32 3
		.amdhsa_float_denorm_mode_16_64 3
		.amdhsa_dx10_clamp 1
		.amdhsa_ieee_mode 1
		.amdhsa_fp16_overflow 0
		.amdhsa_tg_split 0
		.amdhsa_exception_fp_ieee_invalid_op 0
		.amdhsa_exception_fp_denorm_src 0
		.amdhsa_exception_fp_ieee_div_zero 0
		.amdhsa_exception_fp_ieee_overflow 0
		.amdhsa_exception_fp_ieee_underflow 0
		.amdhsa_exception_fp_ieee_inexact 0
		.amdhsa_exception_int_div_zero 0
	.end_amdhsa_kernel

; __global__ void __launch_bounds__(NT, 2) mk_fwd(Args args) {
amdhsa.kernels:
  - .agpr_count:     0
    .args:
      - .offset:         0
        .size:           256
        .value_kind:     by_value
      - .offset:         256
        .size:           4
        .value_kind:     hidden_block_count_x
      - .offset:         260
        .size:           4
        .value_kind:     hidden_block_count_y
      - .offset:         264
        .size:           4
        .value_kind:     hidden_block_count_z
      - .offset:         268
        .size:           2
        .value_kind:     hidden_group_size_x
      - .offset:         270
        .size:           2
        .value_kind:     hidden_group_size_y
      - .offset:         272
        .size:           2
        .value_kind:     hidden_group_size_z
      - .offset:         274
        .size:           2
        .value_kind:     hidden_remainder_x
      - .offset:         276
        .size:           2
        .value_kind:     hidden_remainder_y
      - .offset:         278
        .size:           2
        .value_kind:     hidden_remainder_z
      - .offset:         296
        .size:           8
        .value_kind:     hidden_global_offset_x
      - .offset:         304
        .size:           8
        .value_kind:     hidden_global_offset_y
      - .offset:         312
        .size:           8
        .value_kind:     hidden_global_offset_z
      - .offset:         320
        .size:           2
        .value_kind:     hidden_grid_dims
      - .offset:         344
        .size:           8
        .value_kind:     hidden_multigrid_sync_arg
      - .offset:         376
        .size:           4
        .value_kind:     hidden_dynamic_lds_size
    .group_segment_fixed_size: 0
    .kernarg_segment_align: 8
    .kernarg_segment_size: 512
    .language:       OpenCL C
    .language_version:
      - 2
      - 0
    .max_flat_workgroup_size: 512
    .name:           _Z6mk_fwd4Args
    .private_segment_fixed_size: 0
    .sgpr_count:     108
    .sgpr_spill_count: 53
    .symbol:         _Z6mk_fwd4Args.kd
    .uniform_work_group_size: 1
    .uses_dynamic_stack: false
    .vgpr_count:     250
    .vgpr_spill_count: 0
    .wavefront_size: 64
